# placement: FFN epilogue shifted by +4 bytes on top of M3
# speedup vs baseline: 1.0064x; 1.0064x over previous
; __device__ __forceinline__ void epilogue(const f32x4 (&acc)[2][2][4][2], const Call& C, const Unit& u, int wr, int wc, int fr_, int fq_, int lane, int wid, const Args& a, LAS unsigned char* pst) {
;     ...
;     if (u.slice >= 0) epi_slab_h(acc, J, u, wr, wc, fr, fq);
;     else if (J.kind == K_FUSE) epi_fuse(acc, a, J, u.pm, u.pn, wr, wc, fr, fq, wid, lane, pst);
;     else if (J.kind == K_PLAIN) epi_plain(acc, J, J.row0 + u.pm * BM, J.col0 + u.pn * BM, wr, wc, fr, fq);
;     else if (J.kind == K_DFT) epi_plain(acc, J, J.row0 + ((u.pn >> 1) * J.p0 + u.pm) * BM, J.col0 + (u.pn & 1) * BM, wr, wc, fr, fq);
;     else if (J.kind == K_ROPE) epi_rope(acc, J, J.row0 + u.pm * BM, J.col0 + u.pn * BM, wr, wc, fr, fq);
;     else if (J.kind == K_VT) epi_vt(acc, J, u.pm, u.pn, wr, wc, fr, fq);
;     else epi_ffn(acc, J, J.row0 + u.pm * BM, u.pn, wr, wc, fr, fq, lane);
.LBB0_409:
.LBB0_410:
	s_andn2_b64 vcc, exec, s[0:1]
	s_cbranch_vccnz .LBB0_317
	s_nop 0

; __device__ __forceinline__ float silu_s(float xs) { return xs * __builtin_amdgcn_rcpf(1.0f + __builtin_amdgcn_exp2f(xs)); }
; __device__ __forceinline__ u32x4 pack8(const f32x4& a, const f32x4& b) { u32x4 w; w.x = cvt_pk_bf16(a[0], a[1]); w.y = cvt_pk_bf16(a[2], a[3]); w.z = cvt_pk_bf16(b[0], b[1]); w.w = cvt_pk_bf16(b[2], b[3]); return w; }
; __device__ __forceinline__ void epi_ffn(const f32x4 (&acc)[2][2][4][2], const Job& J, int rowt, int pn, int wr, int wc, int fr, int fq, int lane) {
;     ...
;             if (first || last) {
;                 typedef _Float16 sh4 __attribute__((ext_vector_type(4))); typedef _Float16 sh8 __attribute__((ext_vector_type(8)));
;                 _Float16* sp = SIDE + ((size_t)(blk * 2 + (last ? 1 : 0)) * 3) * DFF + col;
;                 auto pk = [](const f32x4& a, const f32x4& b) { const sh4 x = __builtin_convertvector(a, sh4), y = __builtin_convertvector(b, sh4); return (sh8){x[0], x[1], x[2], x[3], y[0], y[1], y[2], y[3]}; };
;                 *(sh8*)sp = pk(cv[m][0] * NEG_LN2, cv[m][1] * NEG_LN2); *(sh8*)(sp + DFF) = pk(acc[ai][0][m][0], acc[ai][0][m][1]); *(sh8*)(sp + 2 * DFF) = pk(acc[ai][1][m][0], acc[ai][1][m][1]);
;             } else {
;                 f32x4 a0, a1;
; #pragma unroll
;                 for (int e = 0; e < 4; ++e) { a0[e] = silu_s(cv[m][0][e]) * acc[ai][1][m][0][e]; a1[e] = silu_s(cv[m][1][e]) * acc[ai][1][m][1][e]; }
;                 *(u32x4*)(O + (size_t)grow * DFF + col) = pack8(a0, a1);
;             }
;         }
.LBB0_427:
	s_or_b64 exec, exec, s[0:1]
	s_branch .LBB0_433
	s_nop 0
